# MLA loop: P conversion moved ahead of the last two row-sum adds so no pad is needed before each PV MFMA (4 s_nop per tile removed)
# baseline (speedup 1.0000x reference)
; #define MFMA(a, b, c) __builtin_amdgcn_mfma_f32_32x32x16_bf16((a), (b), (c), 0, 0, 0)
; DI unsigned pk2(float lo, float hi) { f32x2 v = {lo, hi}; b16x2 r = __builtin_convertvector(v, b16x2); return __builtin_bit_cast(unsigned, r); }
; template <int MODE>
; DI void attn_item(const Params& p, int layer, int bh, int qb, char* lds) {
;     ...
;         for (int sub = 0; sub < 2; ++sub) {
; #pragma unroll
;           for (int st = 0; st < QS; ++st) {
;             bf16x8 kf = *(const bf16x8*)(Ks + (32 * sub + l32) * KSTR + ((mp * QS + st) * 16 + hh * 8) * 2);
;             if (st == 0) s[sub] = MFMA(kf, qf[mp][st], c0tile); else s[sub] = MFMA(kf, qf[mp][st], s[sub]);
;           }
;     ...
;         auto smpass = [&]() {
;           ps = 0.f;
; #pragma unroll
;           for (int sub = 0; sub < 2; ++sub)
; #pragma unroll
;             for (int ks = 0; ks < 2; ++ks)
; #pragma unroll
;               for (int i = 0; i < 4; ++i) {
;                 const float p0 = __builtin_amdgcn_exp2f(s[sub][8 * ks + 2 * i]), p1 = __builtin_amdgcn_exp2f(s[sub][8 * ks + 2 * i + 1]);
;                 ps += p0 + p1; pk[mp][sub][ks][i] = pk2(p0, p1);
;               }
;         };
;         if (first) rebase();
;         smpass();
;         if (!first && __any(!(ps <= PSLIM))) { rebase(); smpass(); }
;         l[mp] += ps;
;         __builtin_amdgcn_sched_barrier(0);
;       }
; #pragma unroll
;       for (int sub = 0; sub < 2; ++sub) {
;         s16x4 vv[8];
;         if (NMAP == 1) {
; #pragma unroll
;           for (int i = 0; i < 8; ++i) vv[i] = vpre[sub * 8 + i];
;         } else {
;           if (sub == 0) trread8<0>(vaddr, vv); else trread8<32 * VSTR>(vaddr, vv);
;         }
;         __builtin_amdgcn_s_setprio(1);
; #pragma unroll
;         for (int ks = 0; ks < 2; ++ks) {
; #pragma unroll
;           for (int dt = 0; dt < 2; ++dt) {
;             s16x4 lo = vv[ks * 4 + dt * 2], hi = vv[ks * 4 + dt * 2 + 1];
;             bf16x8 vf = __builtin_shufflevector(lo, hi, 0, 1, 2, 3, 4, 5, 6, 7);
; #pragma unroll
;             for (int mp = 0; mp < NMAP; ++mp) O[mp][dt] = MFMA(vf, __builtin_bit_cast(bf16x8, pk[mp][sub][ks]), O[mp][dt]);
;           }
;         }
;         __builtin_amdgcn_s_setprio(0);
;         __builtin_amdgcn_sched_barrier(0);
.Lmla_loop:
	ds_read_b128 v[176:179], v200 offset:27648
	ds_read_b128 v[180:183], v200 offset:27680
	ds_read_b128 v[222:225], v200 offset:27712
	s_waitcnt vmcnt(3)
	ds_write_b128 v202, v[96:99] offset:2048
	ds_write_b64 v203, v[100:101] offset:2048
	ds_write_b128 v207, v[188:191] offset:40960
	buffer_load_dwordx4 v[96:99], v187, s[20:23], s62 offen
	buffer_load_dwordx2 v[100:101], v205, s[20:23], s62 offen
	buffer_load_dwordx4 v[188:191], v187, s[12:15], s29 offen
	s_add_u32 s62, s62, 0x3000
	s_add_u32 s29, s29, 0x2000
	v_exp_f32_e32 v0, v64
	v_exp_f32_e32 v1, v65
	v_exp_f32_e32 v2, v66
	v_exp_f32_e32 v3, v67
	v_add_f32_e32 v10, v0, v1
	v_cvt_pk_bf16_f32 v160, v0, v1
	s_waitcnt lgkmcnt(5)
	v_mfma_f32_32x32x16_bf16 v[128:143], v[176:179], v[104:107], v[48:63]
	ds_read_b128 v[226:229], v200 offset:27744
	s_waitcnt lgkmcnt(5)
	v_mfma_f32_32x32x16_bf16 v[128:143], v[180:183], v[108:111], v[128:143]
	ds_read_b64_tr_b16 v[176:177], v201 offset:15360
	ds_read_b64_tr_b16 v[178:179], v201 offset:16896
	v_add_f32_e32 v10, v10, v2
	v_add_f32_e32 v10, v10, v3
	v_cvt_pk_bf16_f32 v161, v2, v3
	s_waitcnt lgkmcnt(6)
	v_mfma_f32_32x32x16_bf16 v[128:143], v[222:225], v[112:115], v[128:143]
	ds_read_b64_tr_b16 v[180:181], v201 offset:15424
	ds_read_b64_tr_b16 v[182:183], v201 offset:16960
	v_exp_f32_e32 v6, v68
	v_exp_f32_e32 v7, v69
	v_exp_f32_e32 v8, v70
	v_exp_f32_e32 v9, v71
	v_add_f32_e32 v10, v10, v6
	s_waitcnt lgkmcnt(4)
	v_mfma_f32_32x32x16_bf16 v[128:143], v[226:229], v[116:119], v[128:143]
	ds_read_b128 v[222:225], v200 offset:27776
	v_add_f32_e32 v10, v10, v7
	v_cvt_pk_bf16_f32 v162, v6, v7
	v_cvt_pk_bf16_f32 v163, v8, v9
	v_add_f32_e32 v10, v10, v8
	v_add_f32_e32 v10, v10, v9
	s_waitcnt lgkmcnt(3)
	v_mfma_f32_32x32x16_bf16 v[32:47], v[176:179], v[160:163], v[32:47]
	ds_read_b128 v[226:229], v200 offset:27808
	v_exp_f32_e32 v0, v72
	v_exp_f32_e32 v1, v73
	v_exp_f32_e32 v2, v74
	s_waitcnt lgkmcnt(2)
	v_mfma_f32_32x32x16_bf16 v[16:31], v[180:183], v[160:163], v[16:31]
	ds_read_b128 v[176:179], v200 offset:34304
	v_exp_f32_e32 v3, v75
	v_add_f32_e32 v11, v0, v1
	v_cvt_pk_bf16_f32 v164, v0, v1
	v_add_f32_e32 v11, v11, v2
	s_waitcnt lgkmcnt(2)
	v_mfma_f32_32x32x16_bf16 v[128:143], v[222:225], v[120:123], v[128:143]
	ds_read_b64_tr_b16 v[180:181], v201 offset:18432
	ds_read_b64_tr_b16 v[182:183], v201 offset:19968
	v_add_f32_e32 v11, v11, v3
	v_cvt_pk_bf16_f32 v165, v2, v3
	v_exp_f32_e32 v6, v76
	v_exp_f32_e32 v7, v77
	s_waitcnt lgkmcnt(3)
	v_mfma_f32_32x32x16_bf16 v[128:143], v[226:229], v[124:127], v[128:143]
	ds_read_b64_tr_b16 v[222:223], v201 offset:18496
	ds_read_b64_tr_b16 v[224:225], v201 offset:20032
	v_exp_f32_e32 v8, v78
	v_exp_f32_e32 v9, v79
	v_add_f32_e32 v11, v11, v6
	v_add_f32_e32 v11, v11, v7
	s_waitcnt lgkmcnt(4)
	v_mfma_f32_32x32x16_bf16 v[144:159], v[176:179], v[104:107], v[48:63]
	ds_read_b128 v[226:229], v200 offset:34336
	v_cvt_pk_bf16_f32 v166, v6, v7
	v_cvt_pk_bf16_f32 v167, v8, v9
	v_add_f32_e32 v11, v11, v8
	v_add_f32_e32 v11, v11, v9
	s_waitcnt lgkmcnt(3)
	v_mfma_f32_32x32x16_bf16 v[32:47], v[180:183], v[164:167], v[32:47]
	ds_read_b128 v[176:179], v200 offset:34368
	v_exp_f32_e32 v0, v80
	v_exp_f32_e32 v1, v81
	v_exp_f32_e32 v2, v82
	s_waitcnt lgkmcnt(2)
	v_mfma_f32_32x32x16_bf16 v[16:31], v[222:225], v[164:167], v[16:31]
	ds_read_b128 v[180:183], v200 offset:34400
	v_exp_f32_e32 v3, v83
	v_add_f32_e32 v12, v0, v1
	v_cvt_pk_bf16_f32 v168, v0, v1
	v_add_f32_e32 v12, v12, v2
	s_waitcnt lgkmcnt(2)
	v_mfma_f32_32x32x16_bf16 v[144:159], v[226:229], v[108:111], v[144:159]
	ds_read_b64_tr_b16 v[222:223], v201 offset:21504
	ds_read_b64_tr_b16 v[224:225], v201 offset:23040
	v_add_f32_e32 v12, v12, v3
	v_cvt_pk_bf16_f32 v169, v2, v3
	v_exp_f32_e32 v6, v84
	v_exp_f32_e32 v7, v85
	s_waitcnt lgkmcnt(3)
	v_mfma_f32_32x32x16_bf16 v[144:159], v[176:179], v[112:115], v[144:159]
	ds_read_b64_tr_b16 v[226:227], v201 offset:21568
	ds_read_b64_tr_b16 v[228:229], v201 offset:23104
	v_exp_f32_e32 v8, v86
	v_exp_f32_e32 v9, v87
	v_add_f32_e32 v12, v12, v6
	v_add_f32_e32 v12, v12, v7
	s_waitcnt lgkmcnt(4)
	v_mfma_f32_32x32x16_bf16 v[144:159], v[180:183], v[116:119], v[144:159]
	ds_read_b128 v[176:179], v200 offset:34432
	v_cvt_pk_bf16_f32 v170, v6, v7
	v_cvt_pk_bf16_f32 v171, v8, v9
	v_add_f32_e32 v12, v12, v8
	v_add_f32_e32 v12, v12, v9
	s_waitcnt lgkmcnt(3)
	v_mfma_f32_32x32x16_bf16 v[32:47], v[222:225], v[168:171], v[32:47]
	ds_read_b128 v[180:183], v200 offset:34464
	v_exp_f32_e32 v0, v88
	v_exp_f32_e32 v1, v89
	v_exp_f32_e32 v2, v90
	v_exp_f32_e32 v3, v91
	s_waitcnt lgkmcnt(2)
	v_mfma_f32_32x32x16_bf16 v[16:31], v[226:229], v[168:171], v[16:31]
	ds_read_b64_tr_b16 v[222:223], v201 offset:24576
	ds_read_b64_tr_b16 v[224:225], v201 offset:26112
	v_add_f32_e32 v13, v0, v1
	v_cvt_pk_bf16_f32 v172, v0, v1
	v_add_f32_e32 v13, v13, v2
	v_add_f32_e32 v13, v13, v3
	v_cvt_pk_bf16_f32 v173, v2, v3
	s_waitcnt lgkmcnt(3)
	v_mfma_f32_32x32x16_bf16 v[144:159], v[176:179], v[120:123], v[144:159]
	ds_read_b64_tr_b16 v[226:227], v201 offset:24640
	ds_read_b64_tr_b16 v[228:229], v201 offset:26176
	v_exp_f32_e32 v6, v92
	v_exp_f32_e32 v7, v93
	v_exp_f32_e32 v8, v94
	v_exp_f32_e32 v9, v95
	v_add_f32_e32 v13, v13, v6
	s_waitcnt lgkmcnt(4)
	v_mfma_f32_32x32x16_bf16 v[144:159], v[180:183], v[124:127], v[144:159]
	v_add_f32_e32 v13, v13, v7
	v_cvt_pk_bf16_f32 v174, v6, v7
	v_cvt_pk_bf16_f32 v175, v8, v9
	v_add_f32_e32 v13, v13, v8
	v_add_f32_e32 v13, v13, v9
	s_waitcnt lgkmcnt(2)
	v_mfma_f32_32x32x16_bf16 v[32:47], v[222:225], v[172:175], v[32:47]
	s_waitcnt lgkmcnt(0)
	v_mfma_f32_32x32x16_bf16 v[16:31], v[226:229], v[172:175], v[16:31]
	v_add_f32_e32 v10, v10, v11
	v_add_f32_e32 v12, v12, v13
	v_add_f32_e32 v10, v10, v12
	v_add_f32_e32 v192, v192, v10
	v_max_f32_e32 v193, v193, v10
	s_waitcnt lgkmcnt(0)
	s_barrier
; #define MFMA(a, b, c) __builtin_amdgcn_mfma_f32_32x32x16_bf16((a), (b), (c), 0, 0, 0)
; DI unsigned pk2(float lo, float hi) { f32x2 v = {lo, hi}; b16x2 r = __builtin_convertvector(v, b16x2); return __builtin_bit_cast(unsigned, r); }
; template <int MODE>
; DI void attn_item(const Params& p, int layer, int bh, int qb, char* lds) {
;     ...
;         for (int sub = 0; sub < 2; ++sub) {
; #pragma unroll
;           for (int st = 0; st < QS; ++st) {
;             bf16x8 kf = *(const bf16x8*)(Ks + (32 * sub + l32) * KSTR + ((mp * QS + st) * 16 + hh * 8) * 2);
;             if (st == 0) s[sub] = MFMA(kf, qf[mp][st], c0tile); else s[sub] = MFMA(kf, qf[mp][st], s[sub]);
;           }
;     ...
;         auto smpass = [&]() {
;           ps = 0.f;
; #pragma unroll
;           for (int sub = 0; sub < 2; ++sub)
; #pragma unroll
;             for (int ks = 0; ks < 2; ++ks)
; #pragma unroll
;               for (int i = 0; i < 4; ++i) {
;                 const float p0 = __builtin_amdgcn_exp2f(s[sub][8 * ks + 2 * i]), p1 = __builtin_amdgcn_exp2f(s[sub][8 * ks + 2 * i + 1]);
;                 ps += p0 + p1; pk[mp][sub][ks][i] = pk2(p0, p1);
;               }
;         };
;         if (first) rebase();
;         smpass();
;         if (!first && __any(!(ps <= PSLIM))) { rebase(); smpass(); }
;         l[mp] += ps;
;         __builtin_amdgcn_sched_barrier(0);
;       }
; #pragma unroll
;       for (int sub = 0; sub < 2; ++sub) {
;         s16x4 vv[8];
;         if (NMAP == 1) {
; #pragma unroll
;           for (int i = 0; i < 8; ++i) vv[i] = vpre[sub * 8 + i];
;         } else {
;           if (sub == 0) trread8<0>(vaddr, vv); else trread8<32 * VSTR>(vaddr, vv);
;         }
;         __builtin_amdgcn_s_setprio(1);
; #pragma unroll
;         for (int ks = 0; ks < 2; ++ks) {
; #pragma unroll
;           for (int dt = 0; dt < 2; ++dt) {
;             s16x4 lo = vv[ks * 4 + dt * 2], hi = vv[ks * 4 + dt * 2 + 1];
;             bf16x8 vf = __builtin_shufflevector(lo, hi, 0, 1, 2, 3, 4, 5, 6, 7);
; #pragma unroll
;             for (int mp = 0; mp < NMAP; ++mp) O[mp][dt] = MFMA(vf, __builtin_bit_cast(bf16x8, pk[mp][sub][ks]), O[mp][dt]);
;           }
;         }
;         __builtin_amdgcn_s_setprio(0);
;         __builtin_amdgcn_sched_barrier(0);
	ds_read_b128 v[176:179], v200 offset:2048
	ds_read_b128 v[180:183], v200 offset:2080
	ds_read_b128 v[222:225], v200 offset:2112
	s_waitcnt vmcnt(3)
	ds_write_b128 v202, v[230:233] offset:27648
	ds_write_b64 v203, v[234:235] offset:27648
	ds_write_b128 v207, v[236:239] offset:15360
	buffer_load_dwordx4 v[230:233], v187, s[20:23], s62 offen
	buffer_load_dwordx2 v[234:235], v205, s[20:23], s62 offen
	buffer_load_dwordx4 v[236:239], v187, s[12:15], s29 offen
	s_add_u32 s62, s62, 0x3000
	s_add_u32 s29, s29, 0x2000
	v_exp_f32_e32 v0, v128
	v_exp_f32_e32 v1, v129
	v_exp_f32_e32 v2, v130
	v_exp_f32_e32 v3, v131
	v_add_f32_e32 v10, v0, v1
	v_cvt_pk_bf16_f32 v160, v0, v1
	s_waitcnt lgkmcnt(5)
	v_mfma_f32_32x32x16_bf16 v[64:79], v[176:179], v[104:107], v[48:63]
	ds_read_b128 v[226:229], v200 offset:2144
	s_waitcnt lgkmcnt(5)
	v_mfma_f32_32x32x16_bf16 v[64:79], v[180:183], v[108:111], v[64:79]
	ds_read_b64_tr_b16 v[176:177], v201 offset:40960
	ds_read_b64_tr_b16 v[178:179], v201 offset:42496
	v_add_f32_e32 v10, v10, v2
	v_add_f32_e32 v10, v10, v3
	v_cvt_pk_bf16_f32 v161, v2, v3
	s_waitcnt lgkmcnt(6)
	v_mfma_f32_32x32x16_bf16 v[64:79], v[222:225], v[112:115], v[64:79]
	ds_read_b64_tr_b16 v[180:181], v201 offset:41024
	ds_read_b64_tr_b16 v[182:183], v201 offset:42560
	v_exp_f32_e32 v6, v132
	v_exp_f32_e32 v7, v133
	v_exp_f32_e32 v8, v134
	v_exp_f32_e32 v9, v135
	v_add_f32_e32 v10, v10, v6
	s_waitcnt lgkmcnt(4)
	v_mfma_f32_32x32x16_bf16 v[64:79], v[226:229], v[116:119], v[64:79]
	ds_read_b128 v[222:225], v200 offset:2176
	v_add_f32_e32 v10, v10, v7
	v_cvt_pk_bf16_f32 v162, v6, v7
	v_cvt_pk_bf16_f32 v163, v8, v9
	v_add_f32_e32 v10, v10, v8
	v_add_f32_e32 v10, v10, v9
	s_waitcnt lgkmcnt(3)
	v_mfma_f32_32x32x16_bf16 v[32:47], v[176:179], v[160:163], v[32:47]
	ds_read_b128 v[226:229], v200 offset:2208
	v_exp_f32_e32 v0, v136
	v_exp_f32_e32 v1, v137
	v_exp_f32_e32 v2, v138
	s_waitcnt lgkmcnt(2)
	v_mfma_f32_32x32x16_bf16 v[16:31], v[180:183], v[160:163], v[16:31]
	ds_read_b128 v[176:179], v200 offset:8704
	v_exp_f32_e32 v3, v139
	v_add_f32_e32 v11, v0, v1
	v_cvt_pk_bf16_f32 v164, v0, v1
	v_add_f32_e32 v11, v11, v2
	s_waitcnt lgkmcnt(2)
	v_mfma_f32_32x32x16_bf16 v[64:79], v[222:225], v[120:123], v[64:79]
	ds_read_b64_tr_b16 v[180:181], v201 offset:44032
	ds_read_b64_tr_b16 v[182:183], v201 offset:45568
	v_add_f32_e32 v11, v11, v3
	v_cvt_pk_bf16_f32 v165, v2, v3
	v_exp_f32_e32 v6, v140
	v_exp_f32_e32 v7, v141
	s_waitcnt lgkmcnt(3)
	v_mfma_f32_32x32x16_bf16 v[64:79], v[226:229], v[124:127], v[64:79]
	ds_read_b64_tr_b16 v[222:223], v201 offset:44096
	ds_read_b64_tr_b16 v[224:225], v201 offset:45632
	v_exp_f32_e32 v8, v142
	v_exp_f32_e32 v9, v143
	v_add_f32_e32 v11, v11, v6
	v_add_f32_e32 v11, v11, v7
	s_waitcnt lgkmcnt(4)
	v_mfma_f32_32x32x16_bf16 v[80:95], v[176:179], v[104:107], v[48:63]
	ds_read_b128 v[226:229], v200 offset:8736
	v_cvt_pk_bf16_f32 v166, v6, v7
	v_cvt_pk_bf16_f32 v167, v8, v9
	v_add_f32_e32 v11, v11, v8
	v_add_f32_e32 v11, v11, v9
	s_waitcnt lgkmcnt(3)
	v_mfma_f32_32x32x16_bf16 v[32:47], v[180:183], v[164:167], v[32:47]
	ds_read_b128 v[176:179], v200 offset:8768
	v_exp_f32_e32 v0, v144
	v_exp_f32_e32 v1, v145
	v_exp_f32_e32 v2, v146
	s_waitcnt lgkmcnt(2)
	v_mfma_f32_32x32x16_bf16 v[16:31], v[222:225], v[164:167], v[16:31]
	ds_read_b128 v[180:183], v200 offset:8800
	v_exp_f32_e32 v3, v147
	v_add_f32_e32 v12, v0, v1
	v_cvt_pk_bf16_f32 v168, v0, v1
	v_add_f32_e32 v12, v12, v2
	s_waitcnt lgkmcnt(2)
	v_mfma_f32_32x32x16_bf16 v[80:95], v[226:229], v[108:111], v[80:95]
	ds_read_b64_tr_b16 v[222:223], v201 offset:47104
	ds_read_b64_tr_b16 v[224:225], v201 offset:48640
	v_add_f32_e32 v12, v12, v3
	v_cvt_pk_bf16_f32 v169, v2, v3
	v_exp_f32_e32 v6, v148
	v_exp_f32_e32 v7, v149
	s_waitcnt lgkmcnt(3)
	v_mfma_f32_32x32x16_bf16 v[80:95], v[176:179], v[112:115], v[80:95]
	ds_read_b64_tr_b16 v[226:227], v201 offset:47168
	ds_read_b64_tr_b16 v[228:229], v201 offset:48704
	v_exp_f32_e32 v8, v150
	v_exp_f32_e32 v9, v151
	v_add_f32_e32 v12, v12, v6
	v_add_f32_e32 v12, v12, v7
	s_waitcnt lgkmcnt(4)
	v_mfma_f32_32x32x16_bf16 v[80:95], v[180:183], v[116:119], v[80:95]
	ds_read_b128 v[176:179], v200 offset:8832
	v_cvt_pk_bf16_f32 v170, v6, v7
	v_cvt_pk_bf16_f32 v171, v8, v9
	v_add_f32_e32 v12, v12, v8
	v_add_f32_e32 v12, v12, v9
	s_waitcnt lgkmcnt(3)
	v_mfma_f32_32x32x16_bf16 v[32:47], v[222:225], v[168:171], v[32:47]
	ds_read_b128 v[180:183], v200 offset:8864
	v_exp_f32_e32 v0, v152
	v_exp_f32_e32 v1, v153
	v_exp_f32_e32 v2, v154
	v_exp_f32_e32 v3, v155
	s_waitcnt lgkmcnt(2)
	v_mfma_f32_32x32x16_bf16 v[16:31], v[226:229], v[168:171], v[16:31]
	ds_read_b64_tr_b16 v[222:223], v201 offset:50176
	ds_read_b64_tr_b16 v[224:225], v201 offset:51712
	v_add_f32_e32 v13, v0, v1
	v_cvt_pk_bf16_f32 v172, v0, v1
	v_add_f32_e32 v13, v13, v2
	v_add_f32_e32 v13, v13, v3
	v_cvt_pk_bf16_f32 v173, v2, v3
	s_waitcnt lgkmcnt(3)
	v_mfma_f32_32x32x16_bf16 v[80:95], v[176:179], v[120:123], v[80:95]
	ds_read_b64_tr_b16 v[226:227], v201 offset:50240
	ds_read_b64_tr_b16 v[228:229], v201 offset:51776
	v_exp_f32_e32 v6, v156
	v_exp_f32_e32 v7, v157
	v_exp_f32_e32 v8, v158
	v_exp_f32_e32 v9, v159
	v_add_f32_e32 v13, v13, v6
	s_waitcnt lgkmcnt(4)
	v_mfma_f32_32x32x16_bf16 v[80:95], v[180:183], v[124:127], v[80:95]
	v_add_f32_e32 v13, v13, v7
	v_cvt_pk_bf16_f32 v174, v6, v7
	v_cvt_pk_bf16_f32 v175, v8, v9
	v_add_f32_e32 v13, v13, v8
	v_add_f32_e32 v13, v13, v9
	s_waitcnt lgkmcnt(2)
	v_mfma_f32_32x32x16_bf16 v[32:47], v[222:225], v[172:175], v[32:47]
	s_waitcnt lgkmcnt(0)
	v_mfma_f32_32x32x16_bf16 v[16:31], v[226:229], v[172:175], v[16:31]
	v_add_f32_e32 v10, v10, v11
	v_add_f32_e32 v12, v12, v13
	v_add_f32_e32 v10, v10, v12
	v_add_f32_e32 v192, v192, v10
	v_max_f32_e32 v193, v193, v10
	s_add_u32 s28, s28, 2
	s_cmpk_lt_u32 s28, 0x80
	s_waitcnt lgkmcnt(0)
	s_barrier
; DI unsigned pk2(float lo, float hi) { f32x2 v = {lo, hi}; b16x2 r = __builtin_convertvector(v, b16x2); return __builtin_bit_cast(unsigned, r); }
; DI float bflo(unsigned w) { return __uint_as_float(w << 16); }
; DI float bfhi(unsigned w) { return __uint_as_float(w & 0xffff0000u); }
; template <int MODE>
; DI void attn_item(const Params& p, int layer, int bh, int qb, char* lds) {
;     ...
;   __syncthreads();
;   const size_t trow = (size_t)b * S + q0w + l32;
;   const u16* grow = (const u16*)(p.ws + OFF_H) + trow * DIN + C_GATE + ocol;
;   u16* orow = (u16*)(p.ws + OFF_OB) + trow * DM + ocol;
;   float inv0 = 1.f / xchg_sum(l[0]);
;   if (MODE == 1) {
;     const float* lm = (const float*)(p.ws + OFF_LAM);
;     const float lam = lm[layer], post = lm[4 + layer];
;     const float inv1 = lam / xchg_sum(l[1]);
;     float ss = 0.f;
; #pragma unroll
;     for (int dt = 0; dt < 2; ++dt)
; #pragma unroll
;       for (int r = 0; r < 16; ++r) { float v = O[0][dt][r] * inv0 - O[NMAP - 1][dt][r] * inv1; O[0][dt][r] = v; ss += v * v; }
;     ss = xchg_sum(ss);
;     inv0 = rsqrtf(ss * (1.f / 64.f) + 1e-6f) * post;
;   }
; #pragma unroll
;   for (int dt = 0; dt < 2; ++dt)
; #pragma unroll
;     for (int g = 0; g < 4; ++g) {
;       const int d = 32 * dt + 8 * g + 4 * hh;
;       u32x2 gw = *(const u32x2*)(grow + d);
;       float v0 = O[0][dt][4 * g + 0] * inv0, v1 = O[0][dt][4 * g + 1] * inv0, v2 = O[0][dt][4 * g + 2] * inv0, v3 = O[0][dt][4 * g + 3] * inv0;
;       if (MODE == 1) { const float* sl = p.subln + layer * 64 + d; v0 *= sl[0]; v1 *= sl[1]; v2 *= sl[2]; v3 *= sl[3]; }
;       v0 *= bflo(gw[0]); v1 *= bfhi(gw[0]); v2 *= bflo(gw[1]); v3 *= bfhi(gw[1]);
;       u32x2 ow = {pk2(v0, v1), pk2(v2, v3)};
;     ...
;       if (MODE == PROBE_ZERO_MODE) { ow[0] = 0u; ow[1] = 0u; }
;     ...
;       *(u32x2*)(orow + d) = ow;
;     }
	s_cbranch_scc1 .Lmla_loop
	s_waitcnt vmcnt(0)
	s_lshl_b64 s[6:7], s[10:11], 13
	v_ashrrev_i32_e32 v187, 31, v186
	v_lshl_add_u64 v[0:1], s[6:7], 0, v[186:187]
	v_or_b32_e32 v0, v0, v204
	v_mov_b32_e32 v2, s34
	v_mov_b32_e32 v3, s35
	v_mad_u64_u32 v[2:3], s[6:7], v0, s64, v[2:3]
	v_mad_i32_i24 v3, v1, s64, v3
	s_lshl_b32 s4, s52, 7
	v_lshl_add_u32 v12, v206, 1, s4
	v_mov_b32_e32 v13, 0
	v_lshl_add_u64 v[6:7], v[2:3], 0, v[12:13]
	s_mov_b64 s[6:7], 0x6058ec0
	v_lshl_add_u64 v[6:7], v[6:7], 0, s[6:7]
	global_load_dwordx2 v[64:65], v[6:7], off offset:0
	global_load_dwordx2 v[66:67], v[6:7], off offset:16
	global_load_dwordx2 v[68:69], v[6:7], off offset:32
	global_load_dwordx2 v[70:71], v[6:7], off offset:48
	global_load_dwordx2 v[72:73], v[6:7], off offset:64
	global_load_dwordx2 v[74:75], v[6:7], off offset:80
	global_load_dwordx2 v[76:77], v[6:7], off offset:96
	global_load_dwordx2 v[78:79], v[6:7], off offset:112
	v_readlane_b32 s6, v254, 49
	v_readlane_b32 s7, v254, 50
	v_lshlrev_b64 v[0:1], 11, v[0:1]
	s_nop 0
	v_lshl_add_u64 v[0:1], s[6:7], 0, v[0:1]
	v_lshl_add_u64 v[8:9], v[0:1], 0, v[12:13]
	v_cmp_nge_f32_e32 vcc, s94, v193
	s_nop 0
	s_cmp_lg_u64 vcc, 0
	s_cselect_b32 s24, 1, 0
	v_mov_b32_e32 v196, s24
	v_lshrrev_b32_e32 v197, 6, v184
	v_lshlrev_b32_e32 v197, 2, v197
	ds_write_b32 v197, v196 offset:0
	s_waitcnt lgkmcnt(0)
	s_barrier
	v_mov_b32_e32 v197, 0
	ds_read_b128 v[176:179], v197 offset:0
	ds_read_b128 v[180:183], v197 offset:16
	v_mov_b32_e32 v2, v192
	s_nop 1
	v_permlane32_swap_b32_e32 v192, v2
	v_add_f32_e32 v2, v192, v2
	v_div_scale_f32 v3, s[4:5], v2, v2, 1.0
	v_rcp_f32_e32 v4, v3
	s_nop 0
	v_fma_f32 v10, -v3, v4, 1.0
	v_fmac_f32_e32 v4, v10, v4
	v_div_scale_f32 v10, vcc, 1.0, v2, 1.0
	v_mul_f32_e32 v11, v10, v4
	v_fma_f32 v12, -v3, v11, v10
	v_fmac_f32_e32 v11, v12, v4
	v_fma_f32 v3, -v3, v11, v10
	s_nop 1
	v_div_fmas_f32 v3, v3, v4, v11
	v_div_fixup_f32 v2, v3, v2, 1.0
	s_waitcnt lgkmcnt(0)
	v_or3_b32 v196, v176, v177, v178
	v_or3_b32 v196, v196, v179, v180
	v_or3_b32 v196, v196, v181, v182
	v_or_b32_e32 v196, v196, v183
	s_nop 0
	v_readfirstlane_b32 s24, v196
	s_barrier
	s_cmp_lg_u32 s24, 0
	s_cbranch_scc1 .Lmla_slow
	s_waitcnt vmcnt(0)
	v_mul_f32_e32 v32, v32, v2
	v_mul_f32_e32 v33, v33, v2
	v_mul_f32_e32 v34, v34, v2
	v_mul_f32_e32 v35, v35, v2
	v_lshlrev_b32_e32 v196, 16, v64
	v_and_b32_e32 v197, 0xffff0000, v64
	v_mul_f32_e32 v32, v32, v196
	v_mul_f32_e32 v33, v33, v197
	v_lshlrev_b32_e32 v196, 16, v65
	v_and_b32_e32 v197, 0xffff0000, v65
	v_mul_f32_e32 v34, v34, v196
	v_mul_f32_e32 v35, v35, v197
	v_cvt_pk_bf16_f32 v32, v32, v33
	v_cvt_pk_bf16_f32 v33, v34, v35
	global_store_dwordx2 v[8:9], v[32:33], off offset:0
	v_mul_f32_e32 v36, v36, v2
	v_mul_f32_e32 v37, v37, v2
	v_mul_f32_e32 v38, v38, v2
	v_mul_f32_e32 v39, v39, v2
	v_lshlrev_b32_e32 v196, 16, v66
	v_and_b32_e32 v197, 0xffff0000, v66
	v_mul_f32_e32 v36, v36, v196
	v_mul_f32_e32 v37, v37, v197
	v_lshlrev_b32_e32 v196, 16, v67
	v_and_b32_e32 v197, 0xffff0000, v67
	v_mul_f32_e32 v38, v38, v196
	v_mul_f32_e32 v39, v39, v197
	v_cvt_pk_bf16_f32 v36, v36, v37
	v_cvt_pk_bf16_f32 v37, v38, v39
	global_store_dwordx2 v[8:9], v[36:37], off offset:16
	v_mul_f32_e32 v40, v40, v2
	v_mul_f32_e32 v41, v41, v2
	v_mul_f32_e32 v42, v42, v2
	v_mul_f32_e32 v43, v43, v2
	v_lshlrev_b32_e32 v196, 16, v68
	v_and_b32_e32 v197, 0xffff0000, v68
	v_mul_f32_e32 v40, v40, v196
	v_mul_f32_e32 v41, v41, v197
	v_lshlrev_b32_e32 v196, 16, v69
	v_and_b32_e32 v197, 0xffff0000, v69
	v_mul_f32_e32 v42, v42, v196
	v_mul_f32_e32 v43, v43, v197
	v_cvt_pk_bf16_f32 v40, v40, v41
	v_cvt_pk_bf16_f32 v41, v42, v43
	global_store_dwordx2 v[8:9], v[40:41], off offset:32
	v_mul_f32_e32 v44, v44, v2
	v_mul_f32_e32 v45, v45, v2
	v_mul_f32_e32 v46, v46, v2
	v_mul_f32_e32 v47, v47, v2
	v_lshlrev_b32_e32 v196, 16, v70
	v_and_b32_e32 v197, 0xffff0000, v70
	v_mul_f32_e32 v44, v44, v196
	v_mul_f32_e32 v45, v45, v197
	v_lshlrev_b32_e32 v196, 16, v71
	v_and_b32_e32 v197, 0xffff0000, v71
	v_mul_f32_e32 v46, v46, v196
	v_mul_f32_e32 v47, v47, v197
	v_cvt_pk_bf16_f32 v44, v44, v45
	v_cvt_pk_bf16_f32 v45, v46, v47
	global_store_dwordx2 v[8:9], v[44:45], off offset:48
	v_mul_f32_e32 v16, v16, v2
	v_mul_f32_e32 v17, v17, v2
	v_mul_f32_e32 v18, v18, v2
	v_mul_f32_e32 v19, v19, v2
	v_lshlrev_b32_e32 v196, 16, v72
	v_and_b32_e32 v197, 0xffff0000, v72
	v_mul_f32_e32 v16, v16, v196
	v_mul_f32_e32 v17, v17, v197
	v_lshlrev_b32_e32 v196, 16, v73
	v_and_b32_e32 v197, 0xffff0000, v73
	v_mul_f32_e32 v18, v18, v196
	v_mul_f32_e32 v19, v19, v197
	v_cvt_pk_bf16_f32 v16, v16, v17
	v_cvt_pk_bf16_f32 v17, v18, v19
	global_store_dwordx2 v[8:9], v[16:17], off offset:64
	v_mul_f32_e32 v20, v20, v2
	v_mul_f32_e32 v21, v21, v2
	v_mul_f32_e32 v22, v22, v2
	v_mul_f32_e32 v23, v23, v2
	v_lshlrev_b32_e32 v196, 16, v74
	v_and_b32_e32 v197, 0xffff0000, v74
	v_mul_f32_e32 v20, v20, v196
	v_mul_f32_e32 v21, v21, v197
	v_lshlrev_b32_e32 v196, 16, v75
	v_and_b32_e32 v197, 0xffff0000, v75
	v_mul_f32_e32 v22, v22, v196
	v_mul_f32_e32 v23, v23, v197
	v_cvt_pk_bf16_f32 v20, v20, v21
	v_cvt_pk_bf16_f32 v21, v22, v23
	global_store_dwordx2 v[8:9], v[20:21], off offset:80
	v_mul_f32_e32 v24, v24, v2
	v_mul_f32_e32 v25, v25, v2
	v_mul_f32_e32 v26, v26, v2
	v_mul_f32_e32 v27, v27, v2
	v_lshlrev_b32_e32 v196, 16, v76
	v_and_b32_e32 v197, 0xffff0000, v76
	v_mul_f32_e32 v24, v24, v196
	v_mul_f32_e32 v25, v25, v197
	v_lshlrev_b32_e32 v196, 16, v77
	v_and_b32_e32 v197, 0xffff0000, v77
	v_mul_f32_e32 v26, v26, v196
	v_mul_f32_e32 v27, v27, v197
	v_cvt_pk_bf16_f32 v24, v24, v25
	v_cvt_pk_bf16_f32 v25, v26, v27
	global_store_dwordx2 v[8:9], v[24:25], off offset:96
	v_mul_f32_e32 v28, v28, v2
	v_mul_f32_e32 v29, v29, v2
	v_mul_f32_e32 v30, v30, v2
	v_mul_f32_e32 v31, v31, v2
	v_lshlrev_b32_e32 v196, 16, v78
	v_and_b32_e32 v197, 0xffff0000, v78
	v_mul_f32_e32 v28, v28, v196
	v_mul_f32_e32 v29, v29, v197
	v_lshlrev_b32_e32 v196, 16, v79
	v_and_b32_e32 v197, 0xffff0000, v79
	v_mul_f32_e32 v30, v30, v196
	v_mul_f32_e32 v31, v31, v197
	v_cvt_pk_bf16_f32 v28, v28, v29
	v_cvt_pk_bf16_f32 v29, v30, v31
	global_store_dwordx2 v[8:9], v[28:29], off offset:112
	s_branch .LBB0_321
